# BUFM (state_pool @ W_mix) jobs moved out of the pre-pass critical path into the idle slot of the 64 workgroups that have no 13th P1c tile (2 jobs each), consumed by P2 after barrier 3
# baseline (speedup 1.0000x reference)
; #define LAS __attribute__((address_space(3)))
; __device__ __forceinline__ void phase_colmax(const Params& p, LAS unsigned char* lds) {
;     ...
;     { int t3 = threadIdx.x; asm volatile("" : "+v"(t3));
;       for (int j = (int)gridDim.x - 1 - (int)blockIdx.x; j < 128; j += gridDim.x) { const int rc = j >> 4, dc = j & 15, g = dc >> 2, d0 = (dc & 3) * 64;
;         mm_tile<false>((LAS float*)lds, t3, p.spool, 1024, rc * 64, 480, g * 256, p.wmix + (size_t)g * 65536, d0, (float*)(p.ws + WS_BUFM), 1024, g * 256 + d0, nullptr); } }
.LBB0_39:
	v_readlane_b32 s2, v230, 0
	v_mov_b32_e32 v2, v0
	v_readlane_b32 s3, v230, 1
	s_load_dword s0, s[2:3], 0x10
	s_nop 0
	s_load_dword s2, s[2:3], 0x0
	s_mov_b32 s31, 0
	s_waitcnt lgkmcnt(0)
	s_lshr_b32 s0, s0, 16
	s_cmp_lg_u32 s0, 0
	s_cselect_b64 s[0:1], -1, 0
	s_cmp_lg_u64 s[0:1], 0
	s_addc_u32 s54, s2, 0
	s_not_b32 s3, s8
	s_cmp_lg_u64 s[0:1], 0
	s_addc_u32 s55, s3, s2
	s_cmpk_gt_i32 s55, 0x7f
	v_writelane_b32 v230, s3, 5
	s_branch .LBB0_74

; #define LAS __attribute__((address_space(3)))
; __device__ __forceinline__ void phase_colmax(const Params& p, LAS unsigned char* lds) {
;     ...
;     { int t3 = threadIdx.x; asm volatile("" : "+v"(t3));
;       for (int j = (int)gridDim.x - 1 - (int)blockIdx.x; j < 128; j += gridDim.x) { const int rc = j >> 4, dc = j & 15, g = dc >> 2, d0 = (dc & 3) * 64;
;         mm_tile<false>((LAS float*)lds, t3, p.spool, 1024, rc * 64, 480, g * 256, p.wmix + (size_t)g * 65536, d0, (float*)(p.ws + WS_BUFM), 1024, g * 256 + d0, nullptr); } }
; __global__ void __launch_bounds__(NTHREADS, 2) fwd_megakernel(Params p) {
;     ...
;           GemmDesc g{(const bf16_t*)(p.ws + WS_H8I), (const bf16_t*)(p.ws + WS_BIN8I - (size_t)4 * 256 * LD8), LD8 / 2, LD8 / 2, 16, nullptr, nullptr}; Sched1c S{G, c}; gemm_phase<2>(lds, g, S, E8); }
;     }
;     xcd_barrier(xb);
.LBB0_637:
	s_cmpk_gt_u32 s8, 63
	s_cbranch_scc1 .Lbufm_done
	s_mov_b64 s[90:91], s[6:7]
	s_mov_b32 s92, s30
	v_readlane_b32 s2, v230, 0
	v_readlane_b32 s3, v230, 1
	s_nop 3
	s_add_u32 s0, s2, 0xffffff80
	s_addc_u32 s1, s3, -1
	s_load_dwordx2 s[40:41], s[0:1], 0x10
	s_load_dwordx2 s[50:51], s[0:1], 0x38
	s_mov_b32 s31, 0
	s_mov_b32 s54, 64
	s_mov_b32 s55, s8
	v_mov_b32_e32 v2, v0
	s_waitcnt lgkmcnt(0)
	v_add_u32_e32 v1, 0x200, v2
	v_ashrrev_i32_e32 v32, 4, v1
	v_lshlrev_b32_e32 v1, 2, v2
	v_and_b32_e32 v1, 60, v1
	v_lshl_add_u32 v7, v1, 2, 0
	s_movk_i32 s0, 0x10c
	v_bfe_u32 v5, v2, 4, 2
	v_mad_u32_u24 v8, v1, s0, v7
	v_ashrrev_i32_e32 v1, 3, v2
	v_ashrrev_i32_e32 v28, 4, v2
	v_and_b32_e32 v9, -16, v1
	v_bfi_b32 v1, -16, v1, v2
	v_lshl_add_u32 v6, v5, 5, 0
	s_movk_i32 s2, 0x110
	v_ashrrev_i32_e32 v29, 31, v28
	v_ashrrev_i32_e32 v33, 31, v32
	v_mad_u64_u32 v[36:37], s[0:1], v1, s2, v[6:7]
	v_and_b32_e32 v3, 15, v2
	v_lshlrev_b64 v[30:31], 10, v[28:29]
	v_lshlrev_b64 v[34:35], 10, v[32:33]
	s_mov_b64 s[0:1], 0x10000
	v_lshrrev_b32_e32 v2, 1, v2
	v_lshl_add_u64 v[38:39], v[30:31], 0, s[0:1]
	v_lshl_add_u64 v[40:41], v[34:35], 0, s[0:1]
	v_and_or_b32 v2, v2, 32, v3
	s_mov_b64 s[0:1], 0x20000
	v_mov_b32_e32 v27, 0
	v_lshl_add_u64 v[42:43], v[30:31], 0, s[0:1]
	v_lshl_add_u64 v[44:45], v[34:35], 0, s[0:1]
	s_mov_b64 s[0:1], 0x30000
	v_lshlrev_b32_e32 v26, 2, v2
	v_lshlrev_b32_e32 v4, 2, v3
	v_mul_lo_u32 v10, v28, s2
	v_lshl_add_u32 v1, v28, 2, v8
	v_mul_lo_u32 v11, v32, s2
	v_lshl_add_u32 v29, v32, 2, v8
	v_mul_u32_u24_e32 v8, 0x110, v2
	v_lshl_add_u64 v[46:47], v[30:31], 0, s[0:1]
	v_lshl_add_u64 v[48:49], v[34:35], 0, s[0:1]
	v_lshl_add_u64 v[2:3], s[26:27], 0, v[26:27]
	s_mov_b64 s[0:1], 0x2ea20000
	v_lshl_or_b32 v33, v5, 2, v9
	v_lshl_add_u64 v[50:51], v[2:3], 0, s[0:1]
	s_lshl_b32 s56, s55, 2
	s_lshl_b32 s57, s54, 2
	s_lshl_b32 s58, s55, 6
	s_lshl_b32 s59, s54, 6
	v_lshlrev_b32_e32 v26, 2, v4
	s_movk_i32 s60, 0x1e0
	s_movk_i32 s61, 0x1df
	s_movk_i32 s62, 0x1de
	s_movk_i32 s63, 0x1dd
	v_add_u32_e32 v37, v7, v10
	v_add_u32_e32 v58, v7, v11
	v_add_u32_e32 v59, v6, v8
	s_branch .LBB0_42

; #define LAS __attribute__((address_space(3)))
; __device__ __forceinline__ void phase_colmax(const Params& p, LAS unsigned char* lds) {
;     ...
;     { int t3 = threadIdx.x; asm volatile("" : "+v"(t3));
;       for (int j = (int)gridDim.x - 1 - (int)blockIdx.x; j < 128; j += gridDim.x) { const int rc = j >> 4, dc = j & 15, g = dc >> 2, d0 = (dc & 3) * 64;
;         mm_tile<false>((LAS float*)lds, t3, p.spool, 1024, rc * 64, 480, g * 256, p.wmix + (size_t)g * 65536, d0, (float*)(p.ws + WS_BUFM), 1024, g * 256 + d0, nullptr); } }
.Lbufm_exit:
	s_mov_b64 s[6:7], s[90:91]
	s_mov_b32 s30, s92
